# SSD inter-chunk group: swizzled LDS addresses formed with one v_xad_u32 each instead of xor+add
# speedup vs baseline: 1.0012x; 1.0012x over previous
; __device__ __forceinline__ f32x16 mfma32(bf16x8 a, bf16x8 b, f32x16 c) { return __builtin_amdgcn_mfma_f32_32x32x16_bf16(a, b, c, 0, 0, 0); }
;     ...
;             for (int ib = 0; ib < 4; ++ib) {
;                 const unsigned ioff = rowoff + (unsigned)ib * 8192u;
;                 f32x16 Ya;
; #pragma unroll
;                 for (int e = 0; e < 16; ++e) Ya[e] = 0.f;
; #pragma unroll
;                 for (int nb = 0; nb < 4; ++nb)
; #pragma unroll
;                     for (int sp = 0; sp < 2; ++sp) Ya = mfma32(pack_acc(H[nb], sp), t_ld44(TA, ioff, rx4, 4 * nb + 2 * sp, h), Ya);
;                 const float ci = cumL[32 * ib + r];
;                 const float mi = (ib == 0) ? mref[0] : (ib == 1) ? mref[1] : (ib == 2) ? mref[2] : mref[3];
.LBB0_432:
	v_lshl_add_u32 v87, s97, 13, v211
	v_add_u32_e32 v68, v87, v107
	v_xad_u32 v70, v107, 16, v87
	ds_read_b64 v[68:69], v68
	ds_read_b64 v[70:71], v70
	v_xad_u32 v144, v107, 32, v87
	v_xad_u32 v146, v107, 48, v87
	ds_read_b64 v[144:145], v144
	ds_read_b64 v[146:147], v146
	v_xad_u32 v148, v107, 64, v87
	s_movk_i32 s100, 0x50
	v_xad_u32 v150, v107, s100, v87
	ds_read_b64 v[148:149], v148
	ds_read_b64 v[150:151], v150
	v_cvt_pk_bf16_f32 v64, v48, v49
	v_cvt_pk_bf16_f32 v65, v50, v51
	v_cvt_pk_bf16_f32 v66, v52, v53
	v_cvt_pk_bf16_f32 v67, v54, v55
	s_movk_i32 s100, 0x60
	v_xad_u32 v154, v107, s100, v87
	s_movk_i32 s100, 0x70
	v_xad_u32 v156, v107, s100, v87
	ds_read_b64 v[154:155], v154
	ds_read_b64 v[156:157], v156
	s_waitcnt lgkmcnt(6)
	v_mfma_f32_32x32x16_bf16 v[64:79], v[64:67], v[68:71], 0
	v_cvt_pk_bf16_f32 v80, v56, v57
	v_cvt_pk_bf16_f32 v81, v58, v59
	v_cvt_pk_bf16_f32 v82, v60, v61
	v_cvt_pk_bf16_f32 v83, v62, v63
	s_movk_i32 s100, 0x80
	v_xad_u32 v216, v107, s100, v87
	s_movk_i32 s100, 0x90
	v_xad_u32 v218, v107, s100, v87
	ds_read_b64 v[216:217], v216
	ds_read_b64 v[218:219], v218
	s_waitcnt lgkmcnt(6)
	v_mfma_f32_32x32x16_bf16 v[64:79], v[80:83], v[144:147], v[64:79]
	v_cvt_pk_bf16_f32 v80, v32, v33
	v_cvt_pk_bf16_f32 v81, v34, v35
	v_cvt_pk_bf16_f32 v82, v36, v37
	v_cvt_pk_bf16_f32 v83, v38, v39
	s_movk_i32 s100, 0xa0
	v_xad_u32 v144, v107, s100, v87
	s_movk_i32 s100, 0xb0
	v_xad_u32 v146, v107, s100, v87
	ds_read_b64 v[144:145], v144
	ds_read_b64 v[146:147], v146
	s_waitcnt lgkmcnt(6)
	v_mfma_f32_32x32x16_bf16 v[64:79], v[80:83], v[148:151], v[64:79]
	v_cvt_pk_bf16_f32 v80, v40, v41
	v_cvt_pk_bf16_f32 v81, v42, v43
	v_cvt_pk_bf16_f32 v82, v44, v45
	v_cvt_pk_bf16_f32 v83, v46, v47
	s_movk_i32 s100, 0xc0
	v_xad_u32 v148, v107, s100, v87
	s_movk_i32 s100, 0xd0
	v_xad_u32 v150, v107, s100, v87
	ds_read_b64 v[148:149], v148
	ds_read_b64 v[150:151], v150
	s_waitcnt lgkmcnt(6)
	v_mfma_f32_32x32x16_bf16 v[64:79], v[80:83], v[154:157], v[64:79]
	v_cvt_pk_bf16_f32 v80, v16, v17
	v_cvt_pk_bf16_f32 v81, v18, v19
	v_cvt_pk_bf16_f32 v82, v20, v21
	v_cvt_pk_bf16_f32 v83, v22, v23
	s_movk_i32 s100, 0xe0
	v_xad_u32 v154, v107, s100, v87
	s_movk_i32 s100, 0xf0
	v_xad_u32 v156, v107, s100, v87
	ds_read_b64 v[154:155], v154
	ds_read_b64 v[156:157], v156
	s_waitcnt lgkmcnt(6)
	v_mfma_f32_32x32x16_bf16 v[64:79], v[80:83], v[216:219], v[64:79]
	v_cvt_pk_bf16_f32 v80, v24, v25
	v_cvt_pk_bf16_f32 v81, v26, v27
	v_cvt_pk_bf16_f32 v82, v28, v29
	v_cvt_pk_bf16_f32 v83, v30, v31
	s_nop 1
	s_waitcnt lgkmcnt(4)
	v_mfma_f32_32x32x16_bf16 v[64:79], v[80:83], v[144:147], v[64:79]
	v_cvt_pk_bf16_f32 v80, v0, v1
	v_cvt_pk_bf16_f32 v81, v2, v3
	v_cvt_pk_bf16_f32 v82, v4, v5
	v_cvt_pk_bf16_f32 v83, v6, v7
	s_nop 1
	s_waitcnt lgkmcnt(2)
	v_mfma_f32_32x32x16_bf16 v[64:79], v[80:83], v[148:151], v[64:79]
	v_cvt_pk_bf16_f32 v80, v8, v9
	v_cvt_pk_bf16_f32 v81, v10, v11
	v_cvt_pk_bf16_f32 v82, v12, v13
	v_cvt_pk_bf16_f32 v83, v14, v15
	s_nop 1
	s_waitcnt lgkmcnt(0)
	v_mfma_f32_32x32x16_bf16 v[64:79], v[80:83], v[154:157], v[64:79]
	s_lshl_b32 s69, s97, 5
	v_or_b32_e32 v87, s69, v99
	v_lshl_add_u32 v80, v87, 2, s76
	ds_read_b32 v89, v80
	s_cmp_lt_i32 s97, 1
	v_mov_b32_e32 v80, s54
	s_cbranch_scc1 .LBB0_437
	s_cmp_lg_u32 s97, 1
	s_cbranch_scc0 .LBB0_435
	s_cmp_eq_u32 s97, 2
	v_mov_b32_e32 v80, s96
	s_cselect_b64 vcc, -1, 0
	v_cndmask_b32_e32 v80, 0, v80, vcc
	s_cbranch_execz .LBB0_436
	s_branch .LBB0_437

; __device__ __forceinline__ f32x16 mfma32(bf16x8 a, bf16x8 b, f32x16 c) { return __builtin_amdgcn_mfma_f32_32x32x16_bf16(a, b, c, 0, 0, 0); }
;     ...
;             for (int ib = 0; ib < 4; ++ib) {
;                 const unsigned ioff = rowoff + (unsigned)ib * 8192u;
;                 f32x16 Ya;
; #pragma unroll
;                 for (int e = 0; e < 16; ++e) Ya[e] = 0.f;
; #pragma unroll
;                 for (int nb = 0; nb < 4; ++nb)
; #pragma unroll
;                     for (int sp = 0; sp < 2; ++sp) Ya = mfma32(pack_acc(H[nb], sp), t_ld44(TA, ioff, rx4, 4 * nb + 2 * sp, h), Ya);
;                 const float ci = cumL[32 * ib + r];
;                 const float mi = (ib == 0) ? mref[0] : (ib == 1) ? mref[1] : (ib == 2) ? mref[2] : mref[3];
.LBB0_454:
	v_lshl_add_u32 v88, s66, 13, v211
	v_add_u32_e32 v68, v88, v107
	v_xad_u32 v70, v107, 16, v88
	ds_read_b64 v[68:69], v68
	ds_read_b64 v[70:71], v70
	v_xad_u32 v84, v107, 32, v88
	v_xad_u32 v86, v107, 48, v88
	ds_read_b64 v[84:85], v84
	ds_read_b64 v[86:87], v86
	v_xad_u32 v220, v107, 64, v88
	s_movk_i32 s100, 0x50
	v_xad_u32 v222, v107, s100, v88
	ds_read_b64 v[220:221], v220
	ds_read_b64 v[222:223], v222
	v_cvt_pk_bf16_f32 v64, v48, v49
	v_cvt_pk_bf16_f32 v65, v50, v51
	v_cvt_pk_bf16_f32 v66, v52, v53
	v_cvt_pk_bf16_f32 v67, v54, v55
	s_movk_i32 s100, 0x60
	v_xad_u32 v224, v107, s100, v88
	s_movk_i32 s100, 0x70
	v_xad_u32 v226, v107, s100, v88
	ds_read_b64 v[224:225], v224
	ds_read_b64 v[226:227], v226
	s_waitcnt lgkmcnt(6)
	v_mfma_f32_32x32x16_bf16 v[64:79], v[64:67], v[68:71], 0
	v_cvt_pk_bf16_f32 v80, v56, v57
	v_cvt_pk_bf16_f32 v81, v58, v59
	v_cvt_pk_bf16_f32 v82, v60, v61
	v_cvt_pk_bf16_f32 v83, v62, v63
	s_movk_i32 s100, 0x80
	v_xad_u32 v128, v107, s100, v88
	s_movk_i32 s100, 0x90
	v_xad_u32 v130, v107, s100, v88
	ds_read_b64 v[128:129], v128
	ds_read_b64 v[130:131], v130
	s_waitcnt lgkmcnt(6)
	v_mfma_f32_32x32x16_bf16 v[64:79], v[80:83], v[84:87], v[64:79]
	v_cvt_pk_bf16_f32 v80, v32, v33
	v_cvt_pk_bf16_f32 v81, v34, v35
	v_cvt_pk_bf16_f32 v82, v36, v37
	v_cvt_pk_bf16_f32 v83, v38, v39
	s_movk_i32 s100, 0xa0
	v_xad_u32 v84, v107, s100, v88
	s_movk_i32 s100, 0xb0
	v_xad_u32 v86, v107, s100, v88
	ds_read_b64 v[84:85], v84
	ds_read_b64 v[86:87], v86
	s_waitcnt lgkmcnt(6)
	v_mfma_f32_32x32x16_bf16 v[64:79], v[80:83], v[220:223], v[64:79]
	v_cvt_pk_bf16_f32 v80, v40, v41
	v_cvt_pk_bf16_f32 v81, v42, v43
	v_cvt_pk_bf16_f32 v82, v44, v45
	v_cvt_pk_bf16_f32 v83, v46, v47
	s_movk_i32 s100, 0xc0
	v_xad_u32 v220, v107, s100, v88
	s_movk_i32 s100, 0xd0
	v_xad_u32 v222, v107, s100, v88
	ds_read_b64 v[220:221], v220
	ds_read_b64 v[222:223], v222
	s_waitcnt lgkmcnt(6)
	v_mfma_f32_32x32x16_bf16 v[64:79], v[80:83], v[224:227], v[64:79]
	v_cvt_pk_bf16_f32 v80, v16, v17
	v_cvt_pk_bf16_f32 v81, v18, v19
	v_cvt_pk_bf16_f32 v82, v20, v21
	v_cvt_pk_bf16_f32 v83, v22, v23
	s_movk_i32 s100, 0xe0
	v_xad_u32 v224, v107, s100, v88
	s_movk_i32 s100, 0xf0
	v_xad_u32 v226, v107, s100, v88
	ds_read_b64 v[224:225], v224
	ds_read_b64 v[226:227], v226
	s_waitcnt lgkmcnt(6)
	v_mfma_f32_32x32x16_bf16 v[64:79], v[80:83], v[128:131], v[64:79]
	v_cvt_pk_bf16_f32 v80, v24, v25
	v_cvt_pk_bf16_f32 v81, v26, v27
	v_cvt_pk_bf16_f32 v82, v28, v29
	v_cvt_pk_bf16_f32 v83, v30, v31
	s_nop 1
	s_waitcnt lgkmcnt(4)
	v_mfma_f32_32x32x16_bf16 v[64:79], v[80:83], v[84:87], v[64:79]
	v_cvt_pk_bf16_f32 v80, v0, v1
	v_cvt_pk_bf16_f32 v81, v2, v3
	v_cvt_pk_bf16_f32 v82, v4, v5
	v_cvt_pk_bf16_f32 v83, v6, v7
	s_nop 1
	s_waitcnt lgkmcnt(2)
	v_mfma_f32_32x32x16_bf16 v[64:79], v[80:83], v[220:223], v[64:79]
	v_cvt_pk_bf16_f32 v80, v8, v9
	v_cvt_pk_bf16_f32 v81, v10, v11
	v_cvt_pk_bf16_f32 v82, v12, v13
	v_cvt_pk_bf16_f32 v83, v14, v15
	s_nop 1
	s_waitcnt lgkmcnt(0)
	v_mfma_f32_32x32x16_bf16 v[64:79], v[80:83], v[224:227], v[64:79]
	s_lshl_b32 s59, s66, 5
	v_or_b32_e32 v137, s59, v99
	v_lshl_add_u32 v80, v137, 2, s76
	ds_read_b32 v139, v80
	s_cmp_lt_i32 s66, 1
	s_cbranch_scc1 .LBB0_458
	s_cmp_eq_u32 s66, 1
	s_mov_b64 s[62:63], -1
	s_cbranch_scc0 .LBB0_457
	s_mov_b64 s[62:63], 0
